# attention selected loop: staged K/V rows of the next block written to the idle LDS buffer before the exp/PV section instead of after the last PV MFMA
# speedup vs baseline: 1.0375x; 1.0151x over previous
.LBB0_1459:
	s_max_i32 s0, s19, 0
	s_lshl_b32 s76, s0, 6
	v_lshl_add_u64 v[66:67], v[152:153], 0, s[76:77]
	v_mad_u64_u32 v[70:71], s[0:1], v66, s33, v[106:107]
	v_mad_i32_i24 v71, v67, s33, v71
	global_load_dwordx4 v[66:69], v[70:71], off offset:1024
	s_nop 0
	global_load_dwordx4 v[70:73], v[70:71], off offset:1152
	s_max_i32 s98, s7, 0
	s_lshr_b32 s98, s98, 3
	s_and_b32 s98, s98, 0x1ffffffc
	v_add_u32_e32 v244, s98, v157
	ds_read_b32 v243, v244 offset:16
	s_and_b32 s16, s18, 31
	s_mov_b32 s9, s19
	v_lshrrev_b32_e32 v75, s18, v242
	v_and_b32_e32 v75, 1, v75
	v_bfe_u32 v74, v242, s16, 1
	v_cmp_eq_u32_e64 s[0:1], 1, v75
	v_cmp_ne_u32_e32 vcc, 0, v74
	s_cbranch_vccz .LBB0_1463
	ds_read_b128 v[120:123], v114
	ds_read_b128 v[124:127], v114 offset:2560
	ds_read_b128 v[128:131], v114 offset:5120
	ds_read_b128 v[132:135], v114 offset:7680
	ds_read_b128 v[136:139], v114 offset:64
	ds_read_b128 v[140:143], v114 offset:2624
	ds_read_b128 v[176:179], v114 offset:5184
	ds_read_b128 v[180:183], v114 offset:7744
	v_lshl_add_u32 v74, s18, 6, v111
	v_cvt_f32_i32_e32 v90, v74
	v_fma_f32 v74, v146, v90, -v109
	v_fma_f32 v90, v148, v90, -v110
	v_cndmask_b32_e64 v89, v173, v74, s[0:1]
	v_cndmask_b32_e64 v105, v173, v90, s[0:1]
	v_fma_f32 v74, v146, s77, v89
	v_fma_f32 v75, v146, s95, v89
	v_fma_f32 v76, v146, s4, v89
	v_fma_f32 v77, v146, s5, v89
	v_fma_f32 v78, v146, s86, v89
	v_fma_f32 v79, v146, s87, v89
	v_fma_f32 v80, v146, s84, v89
	v_fma_f32 v81, v146, s85, v89
	v_fma_f32 v82, v146, s88, v89
	v_fma_f32 v83, v146, s89, v89
	v_fma_f32 v84, v146, s90, v89
	v_fma_f32 v85, v146, s91, v89
	v_fma_f32 v86, v146, s72, v89
	v_fma_f32 v87, v146, s73, v89
	v_fma_f32 v88, v146, s74, v89
	v_fma_f32 v89, v146, s75, v89
	v_fma_f32 v90, v148, s77, v105
	v_fma_f32 v91, v148, s95, v105
	v_fma_f32 v92, v148, s4, v105
	v_fma_f32 v93, v148, s5, v105
	v_fma_f32 v94, v148, s86, v105
	v_fma_f32 v95, v148, s87, v105
	v_fma_f32 v96, v148, s84, v105
	v_fma_f32 v97, v148, s85, v105
	v_fma_f32 v98, v148, s88, v105
	v_fma_f32 v99, v148, s89, v105
	v_fma_f32 v100, v148, s90, v105
	v_fma_f32 v101, v148, s91, v105
	v_fma_f32 v102, v148, s72, v105
	v_fma_f32 v103, v148, s73, v105
	v_fma_f32 v104, v148, s74, v105
	v_fma_f32 v105, v148, s75, v105
	s_setprio 1
	s_waitcnt lgkmcnt(7)
	v_mfma_f32_16x16x32_bf16 v[74:77], v[120:123], v[6:9], v[74:77]
	v_mfma_f32_16x16x32_bf16 v[90:93], v[120:123], v[14:17], v[90:93]
	s_waitcnt lgkmcnt(6)
	v_mfma_f32_16x16x32_bf16 v[78:81], v[124:127], v[6:9], v[78:81]
	v_mfma_f32_16x16x32_bf16 v[94:97], v[124:127], v[14:17], v[94:97]
	s_waitcnt lgkmcnt(5)
	v_mfma_f32_16x16x32_bf16 v[120:123], v[128:131], v[6:9], v[82:85]
	v_mfma_f32_16x16x32_bf16 v[124:127], v[128:131], v[14:17], v[98:101]
	s_waitcnt lgkmcnt(4)
	v_mfma_f32_16x16x32_bf16 v[128:131], v[132:135], v[6:9], v[86:89]
	v_mfma_f32_16x16x32_bf16 v[132:135], v[132:135], v[14:17], v[102:105]
	s_waitcnt lgkmcnt(3)
	v_mfma_f32_16x16x32_bf16 v[102:105], v[136:139], v[2:5], v[74:77]
	v_mfma_f32_16x16x32_bf16 v[86:89], v[136:139], v[10:13], v[90:93]
	s_waitcnt lgkmcnt(2)
	v_mfma_f32_16x16x32_bf16 v[98:101], v[140:143], v[2:5], v[78:81]
	v_mfma_f32_16x16x32_bf16 v[82:85], v[140:143], v[10:13], v[94:97]
	s_waitcnt lgkmcnt(1)
	v_mfma_f32_16x16x32_bf16 v[94:97], v[176:179], v[2:5], v[120:123]
	v_mfma_f32_16x16x32_bf16 v[78:81], v[176:179], v[10:13], v[124:127]
	s_waitcnt lgkmcnt(0)
	v_mfma_f32_16x16x32_bf16 v[90:93], v[180:183], v[2:5], v[128:131]
	v_mfma_f32_16x16x32_bf16 v[74:77], v[180:183], v[10:13], v[132:135]
	s_setprio 0
	v_max3_f32 v120, v102, s96, v103
	v_max3_f32 v120, v120, v104, v105
	v_max3_f32 v120, v120, v98, v99
	v_max3_f32 v120, v120, v100, v101
	v_max3_f32 v120, v120, v94, v95
	v_max3_f32 v120, v120, v96, v97
	v_max3_f32 v120, v120, v90, v91
	v_max3_f32 v121, v120, v92, v93
	v_max3_f32 v120, v121, v86, v87
	v_max3_f32 v120, v120, v88, v89
	v_max3_f32 v120, v120, v82, v83
	v_max3_f32 v120, v120, v84, v85
	v_max3_f32 v120, v120, v78, v79
	v_max3_f32 v120, v120, v80, v81
	v_max3_f32 v120, v120, v74, v75
	v_max3_f32 v120, v120, v76, v77
	s_mov_b32 s0, 0x41000000
	v_cmp_lt_f32_e32 vcc, s0, v120
	s_cbranch_vccnz .LBB0_1482
	v_cmp_lt_f32_e32 vcc, s94, v120
	s_cbranch_vccz .LBB0_1463
.LBB0_1462:
	s_waitcnt vmcnt(2)
	s_cmp_lt_i32 s7, 0
	s_cbranch_scc1 .Lmy_ew1
	ds_write_b128 v115, v[18:21]
	ds_write_b128 v116, v[22:25]
.Lmy_ew1:
	v_exp_f32_e32 v98, v98
	v_exp_f32_e32 v99, v99
	v_exp_f32_e32 v100, v100
	v_exp_f32_e32 v101, v101
	v_exp_f32_e32 v82, v82
	v_exp_f32_e32 v83, v83
	v_exp_f32_e32 v84, v84
	v_exp_f32_e32 v85, v85
	v_exp_f32_e32 v86, v86
	v_exp_f32_e32 v87, v87
	v_exp_f32_e32 v88, v88
	v_exp_f32_e32 v89, v89
	v_exp_f32_e32 v122, v92
	v_exp_f32_e32 v123, v93
	v_cvt_pk_bf16_f32 v92, v98, v99
	v_cvt_pk_bf16_f32 v93, v100, v101
	v_exp_f32_e32 v78, v78
	v_exp_f32_e32 v79, v79
	v_exp_f32_e32 v80, v80
	v_exp_f32_e32 v81, v81
	v_exp_f32_e32 v98, v74
	v_exp_f32_e32 v99, v75
	v_exp_f32_e32 v100, v76
	v_cvt_pk_bf16_f32 v76, v82, v83
	ds_read_b64_tr_b16 v[82:83], v112 offset:0
	v_exp_f32_e32 v101, v77
	v_cvt_pk_bf16_f32 v77, v84, v85
	ds_read_b64_tr_b16 v[84:85], v112 offset:2560
	v_exp_f32_e32 v102, v102
	v_exp_f32_e32 v103, v103
	v_cvt_pk_bf16_f32 v74, v86, v87
	ds_read_b64_tr_b16 v[86:87], v112 offset:32
	v_exp_f32_e32 v104, v104
	v_exp_f32_e32 v105, v105
	v_cvt_pk_bf16_f32 v75, v88, v89
	ds_read_b64_tr_b16 v[88:89], v112 offset:2592
	v_exp_f32_e32 v94, v94
	v_exp_f32_e32 v95, v95
	v_exp_f32_e32 v96, v96
	v_exp_f32_e32 v97, v97
	v_exp_f32_e32 v120, v90
	v_exp_f32_e32 v121, v91
	v_cvt_pk_bf16_f32 v78, v78, v79
	v_cvt_pk_bf16_f32 v79, v80, v81
	v_cvt_pk_bf16_f32 v80, v98, v99
	ds_read_b64_tr_b16 v[98:99], v112 offset:64
	v_cvt_pk_bf16_f32 v81, v100, v101
	ds_read_b64_tr_b16 v[100:101], v112 offset:2624
	v_cvt_pk_bf16_f32 v90, v102, v103
	ds_read_b64_tr_b16 v[102:103], v112 offset:96
	v_cvt_pk_bf16_f32 v91, v104, v105
	ds_read_b64_tr_b16 v[104:105], v112 offset:2656
	v_cvt_pk_bf16_f32 v94, v94, v95
	v_cvt_pk_bf16_f32 v95, v96, v97
	v_cvt_pk_bf16_f32 v96, v120, v121
	ds_read_b64_tr_b16 v[120:121], v112 offset:5120
	v_cvt_pk_bf16_f32 v97, v122, v123
	ds_read_b64_tr_b16 v[122:123], v112 offset:7680
	ds_read_b64_tr_b16 v[124:125], v112 offset:5152
	ds_read_b64_tr_b16 v[126:127], v112 offset:7712
	ds_read_b64_tr_b16 v[128:129], v112 offset:5184
	ds_read_b64_tr_b16 v[130:131], v112 offset:7744
	ds_read_b64_tr_b16 v[132:133], v112 offset:5216
	ds_read_b64_tr_b16 v[134:135], v112 offset:7776
	s_waitcnt lgkmcnt(8)
	s_setprio 1
	s_mov_b32 s82, s80
	s_mov_b32 s83, s80
	v_mfma_f32_16x16x32_bf16 v[50:53], v[82:85], v[90:93], v[50:53]
	s_mov_b32 s81, s80
	s_waitcnt lgkmcnt(0)
	v_mfma_f32_16x16x32_bf16 v[38:41], v[82:85], v[74:77], v[38:41]
	v_mov_b64_e32 v[84:85], s[82:83]
	v_mov_b64_e32 v[82:83], s[80:81]
	v_mfma_f32_16x16x32_bf16 v[54:57], v[86:89], v[90:93], v[54:57]
	v_mfma_f32_16x16x32_bf16 v[34:37], v[86:89], v[74:77], v[34:37]
	v_mfma_f32_16x16x32_bf16 v[46:49], v[98:101], v[90:93], v[46:49]
	v_mfma_f32_16x16x32_bf16 v[30:33], v[98:101], v[74:77], v[30:33]
	v_mfma_f32_16x16x32_bf16 v[42:45], v[102:105], v[90:93], v[42:45]
	v_mfma_f32_16x16x32_bf16 v[26:29], v[102:105], v[74:77], v[26:29]
	v_mfma_f32_16x16x32_bf16 v[62:65], v[82:85], v[90:93], v[62:65]
	v_mfma_f32_16x16x32_bf16 v[58:61], v[82:85], v[74:77], v[58:61]
	v_mfma_f32_16x16x32_bf16 v[50:53], v[120:123], v[94:97], v[50:53]
	v_mfma_f32_16x16x32_bf16 v[38:41], v[120:123], v[78:81], v[38:41]
	v_mfma_f32_16x16x32_bf16 v[54:57], v[124:127], v[94:97], v[54:57]
	v_mfma_f32_16x16x32_bf16 v[34:37], v[124:127], v[78:81], v[34:37]
	v_mfma_f32_16x16x32_bf16 v[46:49], v[128:131], v[94:97], v[46:49]
	v_mfma_f32_16x16x32_bf16 v[30:33], v[128:131], v[78:81], v[30:33]
	v_mfma_f32_16x16x32_bf16 v[42:45], v[132:135], v[94:97], v[42:45]
	v_mfma_f32_16x16x32_bf16 v[26:29], v[132:135], v[78:81], v[26:29]
	v_mfma_f32_16x16x32_bf16 v[62:65], v[82:85], v[94:97], v[62:65]
	v_mfma_f32_16x16x32_bf16 v[58:61], v[82:85], v[78:81], v[58:61]
	s_setprio 0
	s_branch .LBB0_1465

.LBB0_1474:
	s_cmp_lt_i32 s9, 0
	s_cbranch_scc1 .Lmy_ew2
	s_waitcnt vmcnt(2)
	ds_write_b128 v118, v[66:69]
	ds_write_b128 v119, v[70:73]
.Lmy_ew2:
	v_exp_f32_e32 v98, v98
	v_exp_f32_e32 v99, v99
	v_exp_f32_e32 v100, v100
	v_exp_f32_e32 v101, v101
	v_exp_f32_e32 v82, v82
	v_exp_f32_e32 v83, v83
	v_exp_f32_e32 v84, v84
	v_exp_f32_e32 v85, v85
	v_exp_f32_e32 v86, v86
	v_exp_f32_e32 v87, v87
	v_exp_f32_e32 v88, v88
	v_exp_f32_e32 v89, v89
	v_exp_f32_e32 v122, v92
	v_exp_f32_e32 v123, v93
	v_cvt_pk_bf16_f32 v92, v98, v99
	v_cvt_pk_bf16_f32 v93, v100, v101
	v_exp_f32_e32 v78, v78
	v_exp_f32_e32 v79, v79
	v_exp_f32_e32 v80, v80
	v_exp_f32_e32 v81, v81
	v_exp_f32_e32 v98, v74
	v_exp_f32_e32 v99, v75
	v_exp_f32_e32 v100, v76
	v_cvt_pk_bf16_f32 v76, v82, v83
	ds_read_b64_tr_b16 v[82:83], v113 offset:0
	v_exp_f32_e32 v101, v77
	v_cvt_pk_bf16_f32 v77, v84, v85
	ds_read_b64_tr_b16 v[84:85], v113 offset:2560
	v_exp_f32_e32 v102, v102
	v_exp_f32_e32 v103, v103
	v_cvt_pk_bf16_f32 v74, v86, v87
	ds_read_b64_tr_b16 v[86:87], v113 offset:32
	v_exp_f32_e32 v104, v104
	v_exp_f32_e32 v105, v105
	v_cvt_pk_bf16_f32 v75, v88, v89
	ds_read_b64_tr_b16 v[88:89], v113 offset:2592
	v_exp_f32_e32 v94, v94
	v_exp_f32_e32 v95, v95
	v_exp_f32_e32 v96, v96
	v_exp_f32_e32 v97, v97
	v_exp_f32_e32 v120, v90
	v_exp_f32_e32 v121, v91
	v_cvt_pk_bf16_f32 v78, v78, v79
	v_cvt_pk_bf16_f32 v79, v80, v81
	v_cvt_pk_bf16_f32 v80, v98, v99
	ds_read_b64_tr_b16 v[98:99], v113 offset:64
	v_cvt_pk_bf16_f32 v81, v100, v101
	ds_read_b64_tr_b16 v[100:101], v113 offset:2624
	v_cvt_pk_bf16_f32 v90, v102, v103
	ds_read_b64_tr_b16 v[102:103], v113 offset:96
	v_cvt_pk_bf16_f32 v91, v104, v105
	ds_read_b64_tr_b16 v[104:105], v113 offset:2656
	v_cvt_pk_bf16_f32 v94, v94, v95
	v_cvt_pk_bf16_f32 v95, v96, v97
	v_cvt_pk_bf16_f32 v96, v120, v121
	ds_read_b64_tr_b16 v[120:121], v113 offset:5120
	v_cvt_pk_bf16_f32 v97, v122, v123
	ds_read_b64_tr_b16 v[122:123], v113 offset:7680
	ds_read_b64_tr_b16 v[124:125], v113 offset:5152
	ds_read_b64_tr_b16 v[126:127], v113 offset:7712
	ds_read_b64_tr_b16 v[128:129], v113 offset:5184
	ds_read_b64_tr_b16 v[130:131], v113 offset:7744
	ds_read_b64_tr_b16 v[132:133], v113 offset:5216
	ds_read_b64_tr_b16 v[134:135], v113 offset:7776
	s_waitcnt lgkmcnt(8)
	s_setprio 1
	s_mov_b32 s82, s80
	s_mov_b32 s83, s80
	v_mfma_f32_16x16x32_bf16 v[50:53], v[82:85], v[90:93], v[50:53]
	s_mov_b32 s81, s80
	s_waitcnt lgkmcnt(0)
	v_mfma_f32_16x16x32_bf16 v[38:41], v[82:85], v[74:77], v[38:41]
	v_mov_b64_e32 v[84:85], s[82:83]
	v_mov_b64_e32 v[82:83], s[80:81]
	v_mfma_f32_16x16x32_bf16 v[54:57], v[86:89], v[90:93], v[54:57]
	v_mfma_f32_16x16x32_bf16 v[34:37], v[86:89], v[74:77], v[34:37]
	v_mfma_f32_16x16x32_bf16 v[46:49], v[98:101], v[90:93], v[46:49]
	v_mfma_f32_16x16x32_bf16 v[30:33], v[98:101], v[74:77], v[30:33]
	v_mfma_f32_16x16x32_bf16 v[42:45], v[102:105], v[90:93], v[42:45]
	v_mfma_f32_16x16x32_bf16 v[26:29], v[102:105], v[74:77], v[26:29]
	v_mfma_f32_16x16x32_bf16 v[62:65], v[82:85], v[90:93], v[62:65]
	v_mfma_f32_16x16x32_bf16 v[58:61], v[82:85], v[74:77], v[58:61]
	v_mfma_f32_16x16x32_bf16 v[50:53], v[120:123], v[94:97], v[50:53]
	v_mfma_f32_16x16x32_bf16 v[38:41], v[120:123], v[78:81], v[38:41]
	v_mfma_f32_16x16x32_bf16 v[54:57], v[124:127], v[94:97], v[54:57]
	v_mfma_f32_16x16x32_bf16 v[34:37], v[124:127], v[78:81], v[34:37]
	v_mfma_f32_16x16x32_bf16 v[46:49], v[128:131], v[94:97], v[46:49]
	v_mfma_f32_16x16x32_bf16 v[30:33], v[128:131], v[78:81], v[30:33]
	v_mfma_f32_16x16x32_bf16 v[42:45], v[132:135], v[94:97], v[42:45]
	v_mfma_f32_16x16x32_bf16 v[26:29], v[132:135], v[78:81], v[26:29]
	v_mfma_f32_16x16x32_bf16 v[62:65], v[82:85], v[94:97], v[62:65]
	v_mfma_f32_16x16x32_bf16 v[58:61], v[82:85], v[78:81], v[58:61]
	s_setprio 0
	s_cmp_lt_i32 s9, 0
	s_cselect_b64 s[0:1], -1, 0
	s_branch .LBB0_1477
